# union-2: all previous changes plus GEMM-phase prologue de-serialisation and adaLN GEMV loop with 64 row loads in flight
# speedup vs baseline: 1.0101x; 1.0101x over previous
.LBB0_22:
	global_load_dword v208, v[6:7], off
	v_lshl_add_u64 v[18:19], v[6:7], 0, s[20:21]
	global_load_dword v209, v[18:19], off
	v_lshl_add_u64 v[18:19], v[18:19], 0, s[20:21]
	global_load_dword v210, v[18:19], off
	v_lshl_add_u64 v[18:19], v[18:19], 0, s[20:21]
	global_load_dword v211, v[18:19], off
	v_lshl_add_u64 v[18:19], v[18:19], 0, s[20:21]
	global_load_dword v212, v[18:19], off
	v_lshl_add_u64 v[18:19], v[18:19], 0, s[20:21]
	global_load_dword v213, v[18:19], off
	v_lshl_add_u64 v[18:19], v[18:19], 0, s[20:21]
	global_load_dword v214, v[18:19], off
	v_lshl_add_u64 v[18:19], v[18:19], 0, s[20:21]
	global_load_dword v215, v[18:19], off
	v_lshl_add_u64 v[18:19], v[18:19], 0, s[20:21]
	global_load_dword v216, v[18:19], off
	v_lshl_add_u64 v[18:19], v[18:19], 0, s[20:21]
	global_load_dword v217, v[18:19], off
	v_lshl_add_u64 v[18:19], v[18:19], 0, s[20:21]
	global_load_dword v218, v[18:19], off
	v_lshl_add_u64 v[18:19], v[18:19], 0, s[20:21]
	global_load_dword v219, v[18:19], off
	v_lshl_add_u64 v[18:19], v[18:19], 0, s[20:21]
	global_load_dword v220, v[18:19], off
	v_lshl_add_u64 v[18:19], v[18:19], 0, s[20:21]
	global_load_dword v221, v[18:19], off
	v_lshl_add_u64 v[18:19], v[18:19], 0, s[20:21]
	global_load_dword v222, v[18:19], off
	v_lshl_add_u64 v[18:19], v[18:19], 0, s[20:21]
	global_load_dword v223, v[18:19], off
	v_lshl_add_u64 v[18:19], v[18:19], 0, s[20:21]
	global_load_dword v224, v[18:19], off
	v_lshl_add_u64 v[18:19], v[18:19], 0, s[20:21]
	global_load_dword v225, v[18:19], off
	v_lshl_add_u64 v[18:19], v[18:19], 0, s[20:21]
	global_load_dword v226, v[18:19], off
	v_lshl_add_u64 v[18:19], v[18:19], 0, s[20:21]
	global_load_dword v227, v[18:19], off
	v_lshl_add_u64 v[18:19], v[18:19], 0, s[20:21]
	global_load_dword v228, v[18:19], off
	v_lshl_add_u64 v[18:19], v[18:19], 0, s[20:21]
	global_load_dword v229, v[18:19], off
	v_lshl_add_u64 v[18:19], v[18:19], 0, s[20:21]
	global_load_dword v230, v[18:19], off
	v_lshl_add_u64 v[18:19], v[18:19], 0, s[20:21]
	global_load_dword v231, v[18:19], off
	v_lshl_add_u64 v[18:19], v[18:19], 0, s[20:21]
	global_load_dword v232, v[18:19], off
	v_lshl_add_u64 v[18:19], v[18:19], 0, s[20:21]
	global_load_dword v233, v[18:19], off
	v_lshl_add_u64 v[18:19], v[18:19], 0, s[20:21]
	global_load_dword v234, v[18:19], off
	v_lshl_add_u64 v[18:19], v[18:19], 0, s[20:21]
	global_load_dword v235, v[18:19], off
	v_lshl_add_u64 v[18:19], v[18:19], 0, s[20:21]
	global_load_dword v236, v[18:19], off
	v_lshl_add_u64 v[18:19], v[18:19], 0, s[20:21]
	global_load_dword v237, v[18:19], off
	v_lshl_add_u64 v[18:19], v[18:19], 0, s[20:21]
	global_load_dword v238, v[18:19], off
	v_lshl_add_u64 v[18:19], v[18:19], 0, s[20:21]
	global_load_dword v239, v[18:19], off
	v_lshl_add_u64 v[18:19], v[18:19], 0, s[20:21]
	global_load_dword v240, v[18:19], off
	v_lshl_add_u64 v[18:19], v[18:19], 0, s[20:21]
	global_load_dword v241, v[18:19], off
	v_lshl_add_u64 v[18:19], v[18:19], 0, s[20:21]
	global_load_dword v242, v[18:19], off
	v_lshl_add_u64 v[18:19], v[18:19], 0, s[20:21]
	global_load_dword v243, v[18:19], off
	v_lshl_add_u64 v[18:19], v[18:19], 0, s[20:21]
	global_load_dword v244, v[18:19], off
	v_lshl_add_u64 v[18:19], v[18:19], 0, s[20:21]
	global_load_dword v245, v[18:19], off
	v_lshl_add_u64 v[18:19], v[18:19], 0, s[20:21]
	global_load_dword v182, v[18:19], off
	v_lshl_add_u64 v[18:19], v[18:19], 0, s[20:21]
	global_load_dword v183, v[18:19], off
	v_lshl_add_u64 v[18:19], v[18:19], 0, s[20:21]
	global_load_dword v184, v[18:19], off
	v_lshl_add_u64 v[18:19], v[18:19], 0, s[20:21]
	global_load_dword v185, v[18:19], off
	v_lshl_add_u64 v[18:19], v[18:19], 0, s[20:21]
	global_load_dword v186, v[18:19], off
	v_lshl_add_u64 v[18:19], v[18:19], 0, s[20:21]
	global_load_dword v187, v[18:19], off
	v_lshl_add_u64 v[18:19], v[18:19], 0, s[20:21]
	global_load_dword v188, v[18:19], off
	v_lshl_add_u64 v[18:19], v[18:19], 0, s[20:21]
	global_load_dword v189, v[18:19], off
	v_lshl_add_u64 v[18:19], v[18:19], 0, s[20:21]
	global_load_dword v190, v[18:19], off
	v_lshl_add_u64 v[18:19], v[18:19], 0, s[20:21]
	global_load_dword v191, v[18:19], off
	v_lshl_add_u64 v[18:19], v[18:19], 0, s[20:21]
	global_load_dword v192, v[18:19], off
	v_lshl_add_u64 v[18:19], v[18:19], 0, s[20:21]
	global_load_dword v193, v[18:19], off
	v_lshl_add_u64 v[18:19], v[18:19], 0, s[20:21]
	global_load_dword v194, v[18:19], off
	v_lshl_add_u64 v[18:19], v[18:19], 0, s[20:21]
	global_load_dword v195, v[18:19], off
	v_lshl_add_u64 v[18:19], v[18:19], 0, s[20:21]
	global_load_dword v196, v[18:19], off
	v_lshl_add_u64 v[18:19], v[18:19], 0, s[20:21]
	global_load_dword v197, v[18:19], off
	v_lshl_add_u64 v[18:19], v[18:19], 0, s[20:21]
	global_load_dword v198, v[18:19], off
	v_lshl_add_u64 v[18:19], v[18:19], 0, s[20:21]
	global_load_dword v199, v[18:19], off
	v_lshl_add_u64 v[18:19], v[18:19], 0, s[20:21]
	global_load_dword v200, v[18:19], off
	v_lshl_add_u64 v[18:19], v[18:19], 0, s[20:21]
	global_load_dword v201, v[18:19], off
	v_lshl_add_u64 v[18:19], v[18:19], 0, s[20:21]
	global_load_dword v202, v[18:19], off
	v_lshl_add_u64 v[18:19], v[18:19], 0, s[20:21]
	global_load_dword v203, v[18:19], off
	v_lshl_add_u64 v[18:19], v[18:19], 0, s[20:21]
	global_load_dword v22, v[18:19], off
	v_lshl_add_u64 v[18:19], v[18:19], 0, s[20:21]
	global_load_dword v23, v[18:19], off
	v_lshl_add_u64 v[18:19], v[18:19], 0, s[20:21]
	global_load_dword v24, v[18:19], off
	v_lshl_add_u64 v[18:19], v[18:19], 0, s[20:21]
	global_load_dword v25, v[18:19], off
	s_add_i32 s23, s44, s22
	v_mov_b32_e32 v21, s23
	v_lshl_add_u64 v[6:7], v[6:7], 0, s[12:13]
	v_lshl_add_u64 v[6:7], v[6:7], 0, s[12:13]
	s_addk_i32 s22, 0x800
	ds_read_b128 v[146:149], v21 offset:0
	ds_read_b128 v[150:153], v21 offset:16
	ds_read_b128 v[154:157], v21 offset:32
	ds_read_b128 v[158:161], v21 offset:48
	ds_read_b128 v[162:165], v21 offset:64
	ds_read_b128 v[166:169], v21 offset:80
	ds_read_b128 v[26:29], v21 offset:96
	ds_read_b128 v[30:33], v21 offset:112
	s_waitcnt vmcnt(63) lgkmcnt(6)
	v_pk_fma_f32 v[10:11], v[208:209], v[146:147], v[10:11] op_sel_hi:[0,1,1]
	v_pk_fma_f32 v[14:15], v[208:209], v[148:149], v[14:15] op_sel_hi:[0,1,1]
	v_pk_fma_f32 v[12:13], v[208:209], v[150:151], v[12:13] op_sel_hi:[0,1,1]
	v_pk_fma_f32 v[8:9], v[208:209], v[152:153], v[8:9] op_sel_hi:[0,1,1]
	ds_read_b128 v[146:149], v21 offset:128
	ds_read_b128 v[150:153], v21 offset:144
	s_waitcnt vmcnt(62) lgkmcnt(6)
	v_pk_fma_f32 v[10:11], v[208:209], v[154:155], v[10:11] op_sel:[1,0,0] op_sel_hi:[1,1,1]
	v_pk_fma_f32 v[14:15], v[208:209], v[156:157], v[14:15] op_sel:[1,0,0] op_sel_hi:[1,1,1]
	v_pk_fma_f32 v[12:13], v[208:209], v[158:159], v[12:13] op_sel:[1,0,0] op_sel_hi:[1,1,1]
	v_pk_fma_f32 v[8:9], v[208:209], v[160:161], v[8:9] op_sel:[1,0,0] op_sel_hi:[1,1,1]
	ds_read_b128 v[154:157], v21 offset:160
	ds_read_b128 v[158:161], v21 offset:176
	s_waitcnt vmcnt(61) lgkmcnt(6)
	v_pk_fma_f32 v[10:11], v[210:211], v[162:163], v[10:11] op_sel_hi:[0,1,1]
	v_pk_fma_f32 v[14:15], v[210:211], v[164:165], v[14:15] op_sel_hi:[0,1,1]
	v_pk_fma_f32 v[12:13], v[210:211], v[166:167], v[12:13] op_sel_hi:[0,1,1]
	v_pk_fma_f32 v[8:9], v[210:211], v[168:169], v[8:9] op_sel_hi:[0,1,1]
	ds_read_b128 v[162:165], v21 offset:192
	ds_read_b128 v[166:169], v21 offset:208
	s_waitcnt vmcnt(60) lgkmcnt(6)
	v_pk_fma_f32 v[10:11], v[210:211], v[26:27], v[10:11] op_sel:[1,0,0] op_sel_hi:[1,1,1]
	v_pk_fma_f32 v[14:15], v[210:211], v[28:29], v[14:15] op_sel:[1,0,0] op_sel_hi:[1,1,1]
	v_pk_fma_f32 v[12:13], v[210:211], v[30:31], v[12:13] op_sel:[1,0,0] op_sel_hi:[1,1,1]
	v_pk_fma_f32 v[8:9], v[210:211], v[32:33], v[8:9] op_sel:[1,0,0] op_sel_hi:[1,1,1]
	ds_read_b128 v[26:29], v21 offset:224
	ds_read_b128 v[30:33], v21 offset:240
	s_waitcnt vmcnt(59) lgkmcnt(6)
	v_pk_fma_f32 v[10:11], v[212:213], v[146:147], v[10:11] op_sel_hi:[0,1,1]
	v_pk_fma_f32 v[14:15], v[212:213], v[148:149], v[14:15] op_sel_hi:[0,1,1]
	v_pk_fma_f32 v[12:13], v[212:213], v[150:151], v[12:13] op_sel_hi:[0,1,1]
	v_pk_fma_f32 v[8:9], v[212:213], v[152:153], v[8:9] op_sel_hi:[0,1,1]
	ds_read_b128 v[146:149], v21 offset:256
	ds_read_b128 v[150:153], v21 offset:272
	s_waitcnt vmcnt(58) lgkmcnt(6)
	v_pk_fma_f32 v[10:11], v[212:213], v[154:155], v[10:11] op_sel:[1,0,0] op_sel_hi:[1,1,1]
	v_pk_fma_f32 v[14:15], v[212:213], v[156:157], v[14:15] op_sel:[1,0,0] op_sel_hi:[1,1,1]
	v_pk_fma_f32 v[12:13], v[212:213], v[158:159], v[12:13] op_sel:[1,0,0] op_sel_hi:[1,1,1]
	v_pk_fma_f32 v[8:9], v[212:213], v[160:161], v[8:9] op_sel:[1,0,0] op_sel_hi:[1,1,1]
	ds_read_b128 v[154:157], v21 offset:288
	ds_read_b128 v[158:161], v21 offset:304
	s_waitcnt vmcnt(57) lgkmcnt(6)
	v_pk_fma_f32 v[10:11], v[214:215], v[162:163], v[10:11] op_sel_hi:[0,1,1]
	v_pk_fma_f32 v[14:15], v[214:215], v[164:165], v[14:15] op_sel_hi:[0,1,1]
	v_pk_fma_f32 v[12:13], v[214:215], v[166:167], v[12:13] op_sel_hi:[0,1,1]
	v_pk_fma_f32 v[8:9], v[214:215], v[168:169], v[8:9] op_sel_hi:[0,1,1]
	ds_read_b128 v[162:165], v21 offset:320
	ds_read_b128 v[166:169], v21 offset:336
	s_waitcnt vmcnt(56) lgkmcnt(6)
	v_pk_fma_f32 v[10:11], v[214:215], v[26:27], v[10:11] op_sel:[1,0,0] op_sel_hi:[1,1,1]
	v_pk_fma_f32 v[14:15], v[214:215], v[28:29], v[14:15] op_sel:[1,0,0] op_sel_hi:[1,1,1]
	v_pk_fma_f32 v[12:13], v[214:215], v[30:31], v[12:13] op_sel:[1,0,0] op_sel_hi:[1,1,1]
	v_pk_fma_f32 v[8:9], v[214:215], v[32:33], v[8:9] op_sel:[1,0,0] op_sel_hi:[1,1,1]
	ds_read_b128 v[26:29], v21 offset:352
	ds_read_b128 v[30:33], v21 offset:368
	s_waitcnt vmcnt(55) lgkmcnt(6)
	v_pk_fma_f32 v[10:11], v[216:217], v[146:147], v[10:11] op_sel_hi:[0,1,1]
	v_pk_fma_f32 v[14:15], v[216:217], v[148:149], v[14:15] op_sel_hi:[0,1,1]
	v_pk_fma_f32 v[12:13], v[216:217], v[150:151], v[12:13] op_sel_hi:[0,1,1]
	v_pk_fma_f32 v[8:9], v[216:217], v[152:153], v[8:9] op_sel_hi:[0,1,1]
	ds_read_b128 v[146:149], v21 offset:384
	ds_read_b128 v[150:153], v21 offset:400
	s_waitcnt vmcnt(54) lgkmcnt(6)
	v_pk_fma_f32 v[10:11], v[216:217], v[154:155], v[10:11] op_sel:[1,0,0] op_sel_hi:[1,1,1]
	v_pk_fma_f32 v[14:15], v[216:217], v[156:157], v[14:15] op_sel:[1,0,0] op_sel_hi:[1,1,1]
	v_pk_fma_f32 v[12:13], v[216:217], v[158:159], v[12:13] op_sel:[1,0,0] op_sel_hi:[1,1,1]
	v_pk_fma_f32 v[8:9], v[216:217], v[160:161], v[8:9] op_sel:[1,0,0] op_sel_hi:[1,1,1]
	ds_read_b128 v[154:157], v21 offset:416
	ds_read_b128 v[158:161], v21 offset:432
	s_waitcnt vmcnt(53) lgkmcnt(6)
	v_pk_fma_f32 v[10:11], v[218:219], v[162:163], v[10:11] op_sel_hi:[0,1,1]
	v_pk_fma_f32 v[14:15], v[218:219], v[164:165], v[14:15] op_sel_hi:[0,1,1]
	v_pk_fma_f32 v[12:13], v[218:219], v[166:167], v[12:13] op_sel_hi:[0,1,1]
	v_pk_fma_f32 v[8:9], v[218:219], v[168:169], v[8:9] op_sel_hi:[0,1,1]
	ds_read_b128 v[162:165], v21 offset:448
	ds_read_b128 v[166:169], v21 offset:464
	s_waitcnt vmcnt(52) lgkmcnt(6)
	v_pk_fma_f32 v[10:11], v[218:219], v[26:27], v[10:11] op_sel:[1,0,0] op_sel_hi:[1,1,1]
	v_pk_fma_f32 v[14:15], v[218:219], v[28:29], v[14:15] op_sel:[1,0,0] op_sel_hi:[1,1,1]
	v_pk_fma_f32 v[12:13], v[218:219], v[30:31], v[12:13] op_sel:[1,0,0] op_sel_hi:[1,1,1]
	v_pk_fma_f32 v[8:9], v[218:219], v[32:33], v[8:9] op_sel:[1,0,0] op_sel_hi:[1,1,1]
	ds_read_b128 v[26:29], v21 offset:480
	ds_read_b128 v[30:33], v21 offset:496
	s_waitcnt vmcnt(51) lgkmcnt(6)
	v_pk_fma_f32 v[10:11], v[220:221], v[146:147], v[10:11] op_sel_hi:[0,1,1]
	v_pk_fma_f32 v[14:15], v[220:221], v[148:149], v[14:15] op_sel_hi:[0,1,1]
	v_pk_fma_f32 v[12:13], v[220:221], v[150:151], v[12:13] op_sel_hi:[0,1,1]
	v_pk_fma_f32 v[8:9], v[220:221], v[152:153], v[8:9] op_sel_hi:[0,1,1]
	ds_read_b128 v[146:149], v21 offset:512
	ds_read_b128 v[150:153], v21 offset:528
	s_waitcnt vmcnt(50) lgkmcnt(6)
	v_pk_fma_f32 v[10:11], v[220:221], v[154:155], v[10:11] op_sel:[1,0,0] op_sel_hi:[1,1,1]
	v_pk_fma_f32 v[14:15], v[220:221], v[156:157], v[14:15] op_sel:[1,0,0] op_sel_hi:[1,1,1]
	v_pk_fma_f32 v[12:13], v[220:221], v[158:159], v[12:13] op_sel:[1,0,0] op_sel_hi:[1,1,1]
	v_pk_fma_f32 v[8:9], v[220:221], v[160:161], v[8:9] op_sel:[1,0,0] op_sel_hi:[1,1,1]
	ds_read_b128 v[154:157], v21 offset:544
	ds_read_b128 v[158:161], v21 offset:560
	s_waitcnt vmcnt(49) lgkmcnt(6)
	v_pk_fma_f32 v[10:11], v[222:223], v[162:163], v[10:11] op_sel_hi:[0,1,1]
	v_pk_fma_f32 v[14:15], v[222:223], v[164:165], v[14:15] op_sel_hi:[0,1,1]
	v_pk_fma_f32 v[12:13], v[222:223], v[166:167], v[12:13] op_sel_hi:[0,1,1]
	v_pk_fma_f32 v[8:9], v[222:223], v[168:169], v[8:9] op_sel_hi:[0,1,1]
	ds_read_b128 v[162:165], v21 offset:576
	ds_read_b128 v[166:169], v21 offset:592
	s_waitcnt vmcnt(48) lgkmcnt(6)
	v_pk_fma_f32 v[10:11], v[222:223], v[26:27], v[10:11] op_sel:[1,0,0] op_sel_hi:[1,1,1]
	v_pk_fma_f32 v[14:15], v[222:223], v[28:29], v[14:15] op_sel:[1,0,0] op_sel_hi:[1,1,1]
	v_pk_fma_f32 v[12:13], v[222:223], v[30:31], v[12:13] op_sel:[1,0,0] op_sel_hi:[1,1,1]
	v_pk_fma_f32 v[8:9], v[222:223], v[32:33], v[8:9] op_sel:[1,0,0] op_sel_hi:[1,1,1]
	ds_read_b128 v[26:29], v21 offset:608
	ds_read_b128 v[30:33], v21 offset:624
	s_waitcnt vmcnt(47) lgkmcnt(6)
	v_pk_fma_f32 v[10:11], v[224:225], v[146:147], v[10:11] op_sel_hi:[0,1,1]
	v_pk_fma_f32 v[14:15], v[224:225], v[148:149], v[14:15] op_sel_hi:[0,1,1]
	v_pk_fma_f32 v[12:13], v[224:225], v[150:151], v[12:13] op_sel_hi:[0,1,1]
	v_pk_fma_f32 v[8:9], v[224:225], v[152:153], v[8:9] op_sel_hi:[0,1,1]
	ds_read_b128 v[146:149], v21 offset:640
	ds_read_b128 v[150:153], v21 offset:656
	s_waitcnt vmcnt(46) lgkmcnt(6)
	v_pk_fma_f32 v[10:11], v[224:225], v[154:155], v[10:11] op_sel:[1,0,0] op_sel_hi:[1,1,1]
	v_pk_fma_f32 v[14:15], v[224:225], v[156:157], v[14:15] op_sel:[1,0,0] op_sel_hi:[1,1,1]
	v_pk_fma_f32 v[12:13], v[224:225], v[158:159], v[12:13] op_sel:[1,0,0] op_sel_hi:[1,1,1]
	v_pk_fma_f32 v[8:9], v[224:225], v[160:161], v[8:9] op_sel:[1,0,0] op_sel_hi:[1,1,1]
	ds_read_b128 v[154:157], v21 offset:672
	ds_read_b128 v[158:161], v21 offset:688
	s_waitcnt vmcnt(45) lgkmcnt(6)
	v_pk_fma_f32 v[10:11], v[226:227], v[162:163], v[10:11] op_sel_hi:[0,1,1]
	v_pk_fma_f32 v[14:15], v[226:227], v[164:165], v[14:15] op_sel_hi:[0,1,1]
	v_pk_fma_f32 v[12:13], v[226:227], v[166:167], v[12:13] op_sel_hi:[0,1,1]
	v_pk_fma_f32 v[8:9], v[226:227], v[168:169], v[8:9] op_sel_hi:[0,1,1]
	ds_read_b128 v[162:165], v21 offset:704
	ds_read_b128 v[166:169], v21 offset:720
	s_waitcnt vmcnt(44) lgkmcnt(6)
	v_pk_fma_f32 v[10:11], v[226:227], v[26:27], v[10:11] op_sel:[1,0,0] op_sel_hi:[1,1,1]
	v_pk_fma_f32 v[14:15], v[226:227], v[28:29], v[14:15] op_sel:[1,0,0] op_sel_hi:[1,1,1]
	v_pk_fma_f32 v[12:13], v[226:227], v[30:31], v[12:13] op_sel:[1,0,0] op_sel_hi:[1,1,1]
	v_pk_fma_f32 v[8:9], v[226:227], v[32:33], v[8:9] op_sel:[1,0,0] op_sel_hi:[1,1,1]
	ds_read_b128 v[26:29], v21 offset:736
	ds_read_b128 v[30:33], v21 offset:752
	s_waitcnt vmcnt(43) lgkmcnt(6)
	v_pk_fma_f32 v[10:11], v[228:229], v[146:147], v[10:11] op_sel_hi:[0,1,1]
	v_pk_fma_f32 v[14:15], v[228:229], v[148:149], v[14:15] op_sel_hi:[0,1,1]
	v_pk_fma_f32 v[12:13], v[228:229], v[150:151], v[12:13] op_sel_hi:[0,1,1]
	v_pk_fma_f32 v[8:9], v[228:229], v[152:153], v[8:9] op_sel_hi:[0,1,1]
	ds_read_b128 v[146:149], v21 offset:768
	ds_read_b128 v[150:153], v21 offset:784
	s_waitcnt vmcnt(42) lgkmcnt(6)
	v_pk_fma_f32 v[10:11], v[228:229], v[154:155], v[10:11] op_sel:[1,0,0] op_sel_hi:[1,1,1]
	v_pk_fma_f32 v[14:15], v[228:229], v[156:157], v[14:15] op_sel:[1,0,0] op_sel_hi:[1,1,1]
	v_pk_fma_f32 v[12:13], v[228:229], v[158:159], v[12:13] op_sel:[1,0,0] op_sel_hi:[1,1,1]
	v_pk_fma_f32 v[8:9], v[228:229], v[160:161], v[8:9] op_sel:[1,0,0] op_sel_hi:[1,1,1]
	ds_read_b128 v[154:157], v21 offset:800
	ds_read_b128 v[158:161], v21 offset:816
	s_waitcnt vmcnt(41) lgkmcnt(6)
	v_pk_fma_f32 v[10:11], v[230:231], v[162:163], v[10:11] op_sel_hi:[0,1,1]
	v_pk_fma_f32 v[14:15], v[230:231], v[164:165], v[14:15] op_sel_hi:[0,1,1]
	v_pk_fma_f32 v[12:13], v[230:231], v[166:167], v[12:13] op_sel_hi:[0,1,1]
	v_pk_fma_f32 v[8:9], v[230:231], v[168:169], v[8:9] op_sel_hi:[0,1,1]
	ds_read_b128 v[162:165], v21 offset:832
	ds_read_b128 v[166:169], v21 offset:848
	s_waitcnt vmcnt(40) lgkmcnt(6)
	v_pk_fma_f32 v[10:11], v[230:231], v[26:27], v[10:11] op_sel:[1,0,0] op_sel_hi:[1,1,1]
	v_pk_fma_f32 v[14:15], v[230:231], v[28:29], v[14:15] op_sel:[1,0,0] op_sel_hi:[1,1,1]
	v_pk_fma_f32 v[12:13], v[230:231], v[30:31], v[12:13] op_sel:[1,0,0] op_sel_hi:[1,1,1]
	v_pk_fma_f32 v[8:9], v[230:231], v[32:33], v[8:9] op_sel:[1,0,0] op_sel_hi:[1,1,1]
	ds_read_b128 v[26:29], v21 offset:864
	ds_read_b128 v[30:33], v21 offset:880
	s_waitcnt vmcnt(39) lgkmcnt(6)
	v_pk_fma_f32 v[10:11], v[232:233], v[146:147], v[10:11] op_sel_hi:[0,1,1]
	v_pk_fma_f32 v[14:15], v[232:233], v[148:149], v[14:15] op_sel_hi:[0,1,1]
	v_pk_fma_f32 v[12:13], v[232:233], v[150:151], v[12:13] op_sel_hi:[0,1,1]
	v_pk_fma_f32 v[8:9], v[232:233], v[152:153], v[8:9] op_sel_hi:[0,1,1]
	ds_read_b128 v[146:149], v21 offset:896
	ds_read_b128 v[150:153], v21 offset:912
	s_waitcnt vmcnt(38) lgkmcnt(6)
	v_pk_fma_f32 v[10:11], v[232:233], v[154:155], v[10:11] op_sel:[1,0,0] op_sel_hi:[1,1,1]
	v_pk_fma_f32 v[14:15], v[232:233], v[156:157], v[14:15] op_sel:[1,0,0] op_sel_hi:[1,1,1]
	v_pk_fma_f32 v[12:13], v[232:233], v[158:159], v[12:13] op_sel:[1,0,0] op_sel_hi:[1,1,1]
	v_pk_fma_f32 v[8:9], v[232:233], v[160:161], v[8:9] op_sel:[1,0,0] op_sel_hi:[1,1,1]
	ds_read_b128 v[154:157], v21 offset:928
	ds_read_b128 v[158:161], v21 offset:944
	s_waitcnt vmcnt(37) lgkmcnt(6)
	v_pk_fma_f32 v[10:11], v[234:235], v[162:163], v[10:11] op_sel_hi:[0,1,1]
	v_pk_fma_f32 v[14:15], v[234:235], v[164:165], v[14:15] op_sel_hi:[0,1,1]
	v_pk_fma_f32 v[12:13], v[234:235], v[166:167], v[12:13] op_sel_hi:[0,1,1]
	v_pk_fma_f32 v[8:9], v[234:235], v[168:169], v[8:9] op_sel_hi:[0,1,1]
	ds_read_b128 v[162:165], v21 offset:960
	ds_read_b128 v[166:169], v21 offset:976
	s_waitcnt vmcnt(36) lgkmcnt(6)
	v_pk_fma_f32 v[10:11], v[234:235], v[26:27], v[10:11] op_sel:[1,0,0] op_sel_hi:[1,1,1]
	v_pk_fma_f32 v[14:15], v[234:235], v[28:29], v[14:15] op_sel:[1,0,0] op_sel_hi:[1,1,1]
	v_pk_fma_f32 v[12:13], v[234:235], v[30:31], v[12:13] op_sel:[1,0,0] op_sel_hi:[1,1,1]
	v_pk_fma_f32 v[8:9], v[234:235], v[32:33], v[8:9] op_sel:[1,0,0] op_sel_hi:[1,1,1]
	ds_read_b128 v[26:29], v21 offset:992
	ds_read_b128 v[30:33], v21 offset:1008
	s_waitcnt vmcnt(35) lgkmcnt(6)
	v_pk_fma_f32 v[10:11], v[236:237], v[146:147], v[10:11] op_sel_hi:[0,1,1]
	v_pk_fma_f32 v[14:15], v[236:237], v[148:149], v[14:15] op_sel_hi:[0,1,1]
	v_pk_fma_f32 v[12:13], v[236:237], v[150:151], v[12:13] op_sel_hi:[0,1,1]
	v_pk_fma_f32 v[8:9], v[236:237], v[152:153], v[8:9] op_sel_hi:[0,1,1]
	ds_read_b128 v[146:149], v21 offset:1024
	ds_read_b128 v[150:153], v21 offset:1040
	s_waitcnt vmcnt(34) lgkmcnt(6)
	v_pk_fma_f32 v[10:11], v[236:237], v[154:155], v[10:11] op_sel:[1,0,0] op_sel_hi:[1,1,1]
	v_pk_fma_f32 v[14:15], v[236:237], v[156:157], v[14:15] op_sel:[1,0,0] op_sel_hi:[1,1,1]
	v_pk_fma_f32 v[12:13], v[236:237], v[158:159], v[12:13] op_sel:[1,0,0] op_sel_hi:[1,1,1]
	v_pk_fma_f32 v[8:9], v[236:237], v[160:161], v[8:9] op_sel:[1,0,0] op_sel_hi:[1,1,1]
	ds_read_b128 v[154:157], v21 offset:1056
	ds_read_b128 v[158:161], v21 offset:1072
	s_waitcnt vmcnt(33) lgkmcnt(6)
	v_pk_fma_f32 v[10:11], v[238:239], v[162:163], v[10:11] op_sel_hi:[0,1,1]
	v_pk_fma_f32 v[14:15], v[238:239], v[164:165], v[14:15] op_sel_hi:[0,1,1]
	v_pk_fma_f32 v[12:13], v[238:239], v[166:167], v[12:13] op_sel_hi:[0,1,1]
	v_pk_fma_f32 v[8:9], v[238:239], v[168:169], v[8:9] op_sel_hi:[0,1,1]
	ds_read_b128 v[162:165], v21 offset:1088
	ds_read_b128 v[166:169], v21 offset:1104
	s_waitcnt vmcnt(32) lgkmcnt(6)
	v_pk_fma_f32 v[10:11], v[238:239], v[26:27], v[10:11] op_sel:[1,0,0] op_sel_hi:[1,1,1]
	v_pk_fma_f32 v[14:15], v[238:239], v[28:29], v[14:15] op_sel:[1,0,0] op_sel_hi:[1,1,1]
	v_pk_fma_f32 v[12:13], v[238:239], v[30:31], v[12:13] op_sel:[1,0,0] op_sel_hi:[1,1,1]
	v_pk_fma_f32 v[8:9], v[238:239], v[32:33], v[8:9] op_sel:[1,0,0] op_sel_hi:[1,1,1]
	ds_read_b128 v[26:29], v21 offset:1120
	ds_read_b128 v[30:33], v21 offset:1136
	s_waitcnt vmcnt(31) lgkmcnt(6)
	v_pk_fma_f32 v[10:11], v[240:241], v[146:147], v[10:11] op_sel_hi:[0,1,1]
	v_pk_fma_f32 v[14:15], v[240:241], v[148:149], v[14:15] op_sel_hi:[0,1,1]
	v_pk_fma_f32 v[12:13], v[240:241], v[150:151], v[12:13] op_sel_hi:[0,1,1]
	v_pk_fma_f32 v[8:9], v[240:241], v[152:153], v[8:9] op_sel_hi:[0,1,1]
	ds_read_b128 v[146:149], v21 offset:1152
	ds_read_b128 v[150:153], v21 offset:1168
	s_waitcnt vmcnt(30) lgkmcnt(6)
	v_pk_fma_f32 v[10:11], v[240:241], v[154:155], v[10:11] op_sel:[1,0,0] op_sel_hi:[1,1,1]
	v_pk_fma_f32 v[14:15], v[240:241], v[156:157], v[14:15] op_sel:[1,0,0] op_sel_hi:[1,1,1]
	v_pk_fma_f32 v[12:13], v[240:241], v[158:159], v[12:13] op_sel:[1,0,0] op_sel_hi:[1,1,1]
	v_pk_fma_f32 v[8:9], v[240:241], v[160:161], v[8:9] op_sel:[1,0,0] op_sel_hi:[1,1,1]
	ds_read_b128 v[154:157], v21 offset:1184
	ds_read_b128 v[158:161], v21 offset:1200
	s_waitcnt vmcnt(29) lgkmcnt(6)
	v_pk_fma_f32 v[10:11], v[242:243], v[162:163], v[10:11] op_sel_hi:[0,1,1]
	v_pk_fma_f32 v[14:15], v[242:243], v[164:165], v[14:15] op_sel_hi:[0,1,1]
	v_pk_fma_f32 v[12:13], v[242:243], v[166:167], v[12:13] op_sel_hi:[0,1,1]
	v_pk_fma_f32 v[8:9], v[242:243], v[168:169], v[8:9] op_sel_hi:[0,1,1]
	ds_read_b128 v[162:165], v21 offset:1216
	ds_read_b128 v[166:169], v21 offset:1232
	s_waitcnt vmcnt(28) lgkmcnt(6)
	v_pk_fma_f32 v[10:11], v[242:243], v[26:27], v[10:11] op_sel:[1,0,0] op_sel_hi:[1,1,1]
	v_pk_fma_f32 v[14:15], v[242:243], v[28:29], v[14:15] op_sel:[1,0,0] op_sel_hi:[1,1,1]
	v_pk_fma_f32 v[12:13], v[242:243], v[30:31], v[12:13] op_sel:[1,0,0] op_sel_hi:[1,1,1]
	v_pk_fma_f32 v[8:9], v[242:243], v[32:33], v[8:9] op_sel:[1,0,0] op_sel_hi:[1,1,1]
	ds_read_b128 v[26:29], v21 offset:1248
	ds_read_b128 v[30:33], v21 offset:1264
	s_waitcnt vmcnt(27) lgkmcnt(6)
	v_pk_fma_f32 v[10:11], v[244:245], v[146:147], v[10:11] op_sel_hi:[0,1,1]
	v_pk_fma_f32 v[14:15], v[244:245], v[148:149], v[14:15] op_sel_hi:[0,1,1]
	v_pk_fma_f32 v[12:13], v[244:245], v[150:151], v[12:13] op_sel_hi:[0,1,1]
	v_pk_fma_f32 v[8:9], v[244:245], v[152:153], v[8:9] op_sel_hi:[0,1,1]
	ds_read_b128 v[146:149], v21 offset:1280
	ds_read_b128 v[150:153], v21 offset:1296
	s_waitcnt vmcnt(26) lgkmcnt(6)
	v_pk_fma_f32 v[10:11], v[244:245], v[154:155], v[10:11] op_sel:[1,0,0] op_sel_hi:[1,1,1]
	v_pk_fma_f32 v[14:15], v[244:245], v[156:157], v[14:15] op_sel:[1,0,0] op_sel_hi:[1,1,1]
	v_pk_fma_f32 v[12:13], v[244:245], v[158:159], v[12:13] op_sel:[1,0,0] op_sel_hi:[1,1,1]
	v_pk_fma_f32 v[8:9], v[244:245], v[160:161], v[8:9] op_sel:[1,0,0] op_sel_hi:[1,1,1]
	ds_read_b128 v[154:157], v21 offset:1312
	ds_read_b128 v[158:161], v21 offset:1328
	s_waitcnt vmcnt(25) lgkmcnt(6)
	v_pk_fma_f32 v[10:11], v[182:183], v[162:163], v[10:11] op_sel_hi:[0,1,1]
	v_pk_fma_f32 v[14:15], v[182:183], v[164:165], v[14:15] op_sel_hi:[0,1,1]
	v_pk_fma_f32 v[12:13], v[182:183], v[166:167], v[12:13] op_sel_hi:[0,1,1]
	v_pk_fma_f32 v[8:9], v[182:183], v[168:169], v[8:9] op_sel_hi:[0,1,1]
	ds_read_b128 v[162:165], v21 offset:1344
	ds_read_b128 v[166:169], v21 offset:1360
	s_waitcnt vmcnt(24) lgkmcnt(6)
	v_pk_fma_f32 v[10:11], v[182:183], v[26:27], v[10:11] op_sel:[1,0,0] op_sel_hi:[1,1,1]
	v_pk_fma_f32 v[14:15], v[182:183], v[28:29], v[14:15] op_sel:[1,0,0] op_sel_hi:[1,1,1]
	v_pk_fma_f32 v[12:13], v[182:183], v[30:31], v[12:13] op_sel:[1,0,0] op_sel_hi:[1,1,1]
	v_pk_fma_f32 v[8:9], v[182:183], v[32:33], v[8:9] op_sel:[1,0,0] op_sel_hi:[1,1,1]
	ds_read_b128 v[26:29], v21 offset:1376
	ds_read_b128 v[30:33], v21 offset:1392
	s_waitcnt vmcnt(23) lgkmcnt(6)
	v_pk_fma_f32 v[10:11], v[184:185], v[146:147], v[10:11] op_sel_hi:[0,1,1]
	v_pk_fma_f32 v[14:15], v[184:185], v[148:149], v[14:15] op_sel_hi:[0,1,1]
	v_pk_fma_f32 v[12:13], v[184:185], v[150:151], v[12:13] op_sel_hi:[0,1,1]
	v_pk_fma_f32 v[8:9], v[184:185], v[152:153], v[8:9] op_sel_hi:[0,1,1]
	ds_read_b128 v[146:149], v21 offset:1408
	ds_read_b128 v[150:153], v21 offset:1424
	s_waitcnt vmcnt(22) lgkmcnt(6)
	v_pk_fma_f32 v[10:11], v[184:185], v[154:155], v[10:11] op_sel:[1,0,0] op_sel_hi:[1,1,1]
	v_pk_fma_f32 v[14:15], v[184:185], v[156:157], v[14:15] op_sel:[1,0,0] op_sel_hi:[1,1,1]
	v_pk_fma_f32 v[12:13], v[184:185], v[158:159], v[12:13] op_sel:[1,0,0] op_sel_hi:[1,1,1]
	v_pk_fma_f32 v[8:9], v[184:185], v[160:161], v[8:9] op_sel:[1,0,0] op_sel_hi:[1,1,1]
	ds_read_b128 v[154:157], v21 offset:1440
	ds_read_b128 v[158:161], v21 offset:1456
	s_waitcnt vmcnt(21) lgkmcnt(6)
	v_pk_fma_f32 v[10:11], v[186:187], v[162:163], v[10:11] op_sel_hi:[0,1,1]
	v_pk_fma_f32 v[14:15], v[186:187], v[164:165], v[14:15] op_sel_hi:[0,1,1]
	v_pk_fma_f32 v[12:13], v[186:187], v[166:167], v[12:13] op_sel_hi:[0,1,1]
	v_pk_fma_f32 v[8:9], v[186:187], v[168:169], v[8:9] op_sel_hi:[0,1,1]
	ds_read_b128 v[162:165], v21 offset:1472
	ds_read_b128 v[166:169], v21 offset:1488
	s_waitcnt vmcnt(20) lgkmcnt(6)
	v_pk_fma_f32 v[10:11], v[186:187], v[26:27], v[10:11] op_sel:[1,0,0] op_sel_hi:[1,1,1]
	v_pk_fma_f32 v[14:15], v[186:187], v[28:29], v[14:15] op_sel:[1,0,0] op_sel_hi:[1,1,1]
	v_pk_fma_f32 v[12:13], v[186:187], v[30:31], v[12:13] op_sel:[1,0,0] op_sel_hi:[1,1,1]
	v_pk_fma_f32 v[8:9], v[186:187], v[32:33], v[8:9] op_sel:[1,0,0] op_sel_hi:[1,1,1]
	ds_read_b128 v[26:29], v21 offset:1504
	ds_read_b128 v[30:33], v21 offset:1520
	s_waitcnt vmcnt(19) lgkmcnt(6)
	v_pk_fma_f32 v[10:11], v[188:189], v[146:147], v[10:11] op_sel_hi:[0,1,1]
	v_pk_fma_f32 v[14:15], v[188:189], v[148:149], v[14:15] op_sel_hi:[0,1,1]
	v_pk_fma_f32 v[12:13], v[188:189], v[150:151], v[12:13] op_sel_hi:[0,1,1]
	v_pk_fma_f32 v[8:9], v[188:189], v[152:153], v[8:9] op_sel_hi:[0,1,1]
	ds_read_b128 v[146:149], v21 offset:1536
	ds_read_b128 v[150:153], v21 offset:1552
	s_waitcnt vmcnt(18) lgkmcnt(6)
	v_pk_fma_f32 v[10:11], v[188:189], v[154:155], v[10:11] op_sel:[1,0,0] op_sel_hi:[1,1,1]
	v_pk_fma_f32 v[14:15], v[188:189], v[156:157], v[14:15] op_sel:[1,0,0] op_sel_hi:[1,1,1]
	v_pk_fma_f32 v[12:13], v[188:189], v[158:159], v[12:13] op_sel:[1,0,0] op_sel_hi:[1,1,1]
	v_pk_fma_f32 v[8:9], v[188:189], v[160:161], v[8:9] op_sel:[1,0,0] op_sel_hi:[1,1,1]
	ds_read_b128 v[154:157], v21 offset:1568
	ds_read_b128 v[158:161], v21 offset:1584
	s_waitcnt vmcnt(17) lgkmcnt(6)
	v_pk_fma_f32 v[10:11], v[190:191], v[162:163], v[10:11] op_sel_hi:[0,1,1]
	v_pk_fma_f32 v[14:15], v[190:191], v[164:165], v[14:15] op_sel_hi:[0,1,1]
	v_pk_fma_f32 v[12:13], v[190:191], v[166:167], v[12:13] op_sel_hi:[0,1,1]
	v_pk_fma_f32 v[8:9], v[190:191], v[168:169], v[8:9] op_sel_hi:[0,1,1]
	ds_read_b128 v[162:165], v21 offset:1600
	ds_read_b128 v[166:169], v21 offset:1616
	s_waitcnt vmcnt(16) lgkmcnt(6)
	v_pk_fma_f32 v[10:11], v[190:191], v[26:27], v[10:11] op_sel:[1,0,0] op_sel_hi:[1,1,1]
	v_pk_fma_f32 v[14:15], v[190:191], v[28:29], v[14:15] op_sel:[1,0,0] op_sel_hi:[1,1,1]
	v_pk_fma_f32 v[12:13], v[190:191], v[30:31], v[12:13] op_sel:[1,0,0] op_sel_hi:[1,1,1]
	v_pk_fma_f32 v[8:9], v[190:191], v[32:33], v[8:9] op_sel:[1,0,0] op_sel_hi:[1,1,1]
	ds_read_b128 v[26:29], v21 offset:1632
	ds_read_b128 v[30:33], v21 offset:1648
	s_waitcnt vmcnt(15) lgkmcnt(6)
	v_pk_fma_f32 v[10:11], v[192:193], v[146:147], v[10:11] op_sel_hi:[0,1,1]
	v_pk_fma_f32 v[14:15], v[192:193], v[148:149], v[14:15] op_sel_hi:[0,1,1]
	v_pk_fma_f32 v[12:13], v[192:193], v[150:151], v[12:13] op_sel_hi:[0,1,1]
	v_pk_fma_f32 v[8:9], v[192:193], v[152:153], v[8:9] op_sel_hi:[0,1,1]
	ds_read_b128 v[146:149], v21 offset:1664
	ds_read_b128 v[150:153], v21 offset:1680
	s_waitcnt vmcnt(14) lgkmcnt(6)
	v_pk_fma_f32 v[10:11], v[192:193], v[154:155], v[10:11] op_sel:[1,0,0] op_sel_hi:[1,1,1]
	v_pk_fma_f32 v[14:15], v[192:193], v[156:157], v[14:15] op_sel:[1,0,0] op_sel_hi:[1,1,1]
	v_pk_fma_f32 v[12:13], v[192:193], v[158:159], v[12:13] op_sel:[1,0,0] op_sel_hi:[1,1,1]
	v_pk_fma_f32 v[8:9], v[192:193], v[160:161], v[8:9] op_sel:[1,0,0] op_sel_hi:[1,1,1]
	ds_read_b128 v[154:157], v21 offset:1696
	ds_read_b128 v[158:161], v21 offset:1712
	s_waitcnt vmcnt(13) lgkmcnt(6)
	v_pk_fma_f32 v[10:11], v[194:195], v[162:163], v[10:11] op_sel_hi:[0,1,1]
	v_pk_fma_f32 v[14:15], v[194:195], v[164:165], v[14:15] op_sel_hi:[0,1,1]
	v_pk_fma_f32 v[12:13], v[194:195], v[166:167], v[12:13] op_sel_hi:[0,1,1]
	v_pk_fma_f32 v[8:9], v[194:195], v[168:169], v[8:9] op_sel_hi:[0,1,1]
	ds_read_b128 v[162:165], v21 offset:1728
	ds_read_b128 v[166:169], v21 offset:1744
	s_waitcnt vmcnt(12) lgkmcnt(6)
	v_pk_fma_f32 v[10:11], v[194:195], v[26:27], v[10:11] op_sel:[1,0,0] op_sel_hi:[1,1,1]
	v_pk_fma_f32 v[14:15], v[194:195], v[28:29], v[14:15] op_sel:[1,0,0] op_sel_hi:[1,1,1]
	v_pk_fma_f32 v[12:13], v[194:195], v[30:31], v[12:13] op_sel:[1,0,0] op_sel_hi:[1,1,1]
	v_pk_fma_f32 v[8:9], v[194:195], v[32:33], v[8:9] op_sel:[1,0,0] op_sel_hi:[1,1,1]
	ds_read_b128 v[26:29], v21 offset:1760
	ds_read_b128 v[30:33], v21 offset:1776
	s_waitcnt vmcnt(11) lgkmcnt(6)
	v_pk_fma_f32 v[10:11], v[196:197], v[146:147], v[10:11] op_sel_hi:[0,1,1]
	v_pk_fma_f32 v[14:15], v[196:197], v[148:149], v[14:15] op_sel_hi:[0,1,1]
	v_pk_fma_f32 v[12:13], v[196:197], v[150:151], v[12:13] op_sel_hi:[0,1,1]
	v_pk_fma_f32 v[8:9], v[196:197], v[152:153], v[8:9] op_sel_hi:[0,1,1]
	ds_read_b128 v[146:149], v21 offset:1792
	ds_read_b128 v[150:153], v21 offset:1808
	s_waitcnt vmcnt(10) lgkmcnt(6)
	v_pk_fma_f32 v[10:11], v[196:197], v[154:155], v[10:11] op_sel:[1,0,0] op_sel_hi:[1,1,1]
	v_pk_fma_f32 v[14:15], v[196:197], v[156:157], v[14:15] op_sel:[1,0,0] op_sel_hi:[1,1,1]
	v_pk_fma_f32 v[12:13], v[196:197], v[158:159], v[12:13] op_sel:[1,0,0] op_sel_hi:[1,1,1]
	v_pk_fma_f32 v[8:9], v[196:197], v[160:161], v[8:9] op_sel:[1,0,0] op_sel_hi:[1,1,1]
	ds_read_b128 v[154:157], v21 offset:1824
	ds_read_b128 v[158:161], v21 offset:1840
	s_waitcnt vmcnt(9) lgkmcnt(6)
	v_pk_fma_f32 v[10:11], v[198:199], v[162:163], v[10:11] op_sel_hi:[0,1,1]
	v_pk_fma_f32 v[14:15], v[198:199], v[164:165], v[14:15] op_sel_hi:[0,1,1]
	v_pk_fma_f32 v[12:13], v[198:199], v[166:167], v[12:13] op_sel_hi:[0,1,1]
	v_pk_fma_f32 v[8:9], v[198:199], v[168:169], v[8:9] op_sel_hi:[0,1,1]
	ds_read_b128 v[162:165], v21 offset:1856
	ds_read_b128 v[166:169], v21 offset:1872
	s_waitcnt vmcnt(8) lgkmcnt(6)
	v_pk_fma_f32 v[10:11], v[198:199], v[26:27], v[10:11] op_sel:[1,0,0] op_sel_hi:[1,1,1]
	v_pk_fma_f32 v[14:15], v[198:199], v[28:29], v[14:15] op_sel:[1,0,0] op_sel_hi:[1,1,1]
	v_pk_fma_f32 v[12:13], v[198:199], v[30:31], v[12:13] op_sel:[1,0,0] op_sel_hi:[1,1,1]
	v_pk_fma_f32 v[8:9], v[198:199], v[32:33], v[8:9] op_sel:[1,0,0] op_sel_hi:[1,1,1]
	ds_read_b128 v[26:29], v21 offset:1888
	ds_read_b128 v[30:33], v21 offset:1904
	s_waitcnt vmcnt(7) lgkmcnt(6)
	v_pk_fma_f32 v[10:11], v[200:201], v[146:147], v[10:11] op_sel_hi:[0,1,1]
	v_pk_fma_f32 v[14:15], v[200:201], v[148:149], v[14:15] op_sel_hi:[0,1,1]
	v_pk_fma_f32 v[12:13], v[200:201], v[150:151], v[12:13] op_sel_hi:[0,1,1]
	v_pk_fma_f32 v[8:9], v[200:201], v[152:153], v[8:9] op_sel_hi:[0,1,1]
	ds_read_b128 v[146:149], v21 offset:1920
	ds_read_b128 v[150:153], v21 offset:1936
	s_waitcnt vmcnt(6) lgkmcnt(6)
	v_pk_fma_f32 v[10:11], v[200:201], v[154:155], v[10:11] op_sel:[1,0,0] op_sel_hi:[1,1,1]
	v_pk_fma_f32 v[14:15], v[200:201], v[156:157], v[14:15] op_sel:[1,0,0] op_sel_hi:[1,1,1]
	v_pk_fma_f32 v[12:13], v[200:201], v[158:159], v[12:13] op_sel:[1,0,0] op_sel_hi:[1,1,1]
	v_pk_fma_f32 v[8:9], v[200:201], v[160:161], v[8:9] op_sel:[1,0,0] op_sel_hi:[1,1,1]
	ds_read_b128 v[154:157], v21 offset:1952
	ds_read_b128 v[158:161], v21 offset:1968
	s_waitcnt vmcnt(5) lgkmcnt(6)
	v_pk_fma_f32 v[10:11], v[202:203], v[162:163], v[10:11] op_sel_hi:[0,1,1]
	v_pk_fma_f32 v[14:15], v[202:203], v[164:165], v[14:15] op_sel_hi:[0,1,1]
	v_pk_fma_f32 v[12:13], v[202:203], v[166:167], v[12:13] op_sel_hi:[0,1,1]
	v_pk_fma_f32 v[8:9], v[202:203], v[168:169], v[8:9] op_sel_hi:[0,1,1]
	ds_read_b128 v[162:165], v21 offset:1984
	ds_read_b128 v[166:169], v21 offset:2000
	s_waitcnt vmcnt(4) lgkmcnt(6)
	v_pk_fma_f32 v[10:11], v[202:203], v[26:27], v[10:11] op_sel:[1,0,0] op_sel_hi:[1,1,1]
	v_pk_fma_f32 v[14:15], v[202:203], v[28:29], v[14:15] op_sel:[1,0,0] op_sel_hi:[1,1,1]
	v_pk_fma_f32 v[12:13], v[202:203], v[30:31], v[12:13] op_sel:[1,0,0] op_sel_hi:[1,1,1]
	v_pk_fma_f32 v[8:9], v[202:203], v[32:33], v[8:9] op_sel:[1,0,0] op_sel_hi:[1,1,1]
	ds_read_b128 v[26:29], v21 offset:2016
	ds_read_b128 v[30:33], v21 offset:2032
	s_waitcnt vmcnt(3) lgkmcnt(6)
	v_pk_fma_f32 v[10:11], v[22:23], v[146:147], v[10:11] op_sel_hi:[0,1,1]
	v_pk_fma_f32 v[14:15], v[22:23], v[148:149], v[14:15] op_sel_hi:[0,1,1]
	v_pk_fma_f32 v[12:13], v[22:23], v[150:151], v[12:13] op_sel_hi:[0,1,1]
	v_pk_fma_f32 v[8:9], v[22:23], v[152:153], v[8:9] op_sel_hi:[0,1,1]
	s_waitcnt vmcnt(2) lgkmcnt(4)
	v_pk_fma_f32 v[10:11], v[22:23], v[154:155], v[10:11] op_sel:[1,0,0] op_sel_hi:[1,1,1]
	v_pk_fma_f32 v[14:15], v[22:23], v[156:157], v[14:15] op_sel:[1,0,0] op_sel_hi:[1,1,1]
	v_pk_fma_f32 v[12:13], v[22:23], v[158:159], v[12:13] op_sel:[1,0,0] op_sel_hi:[1,1,1]
	v_pk_fma_f32 v[8:9], v[22:23], v[160:161], v[8:9] op_sel:[1,0,0] op_sel_hi:[1,1,1]
	s_waitcnt vmcnt(1) lgkmcnt(2)
	v_pk_fma_f32 v[10:11], v[24:25], v[162:163], v[10:11] op_sel_hi:[0,1,1]
	v_pk_fma_f32 v[14:15], v[24:25], v[164:165], v[14:15] op_sel_hi:[0,1,1]
	v_pk_fma_f32 v[12:13], v[24:25], v[166:167], v[12:13] op_sel_hi:[0,1,1]
	v_pk_fma_f32 v[8:9], v[24:25], v[168:169], v[8:9] op_sel_hi:[0,1,1]
	s_waitcnt vmcnt(0) lgkmcnt(0)
	v_pk_fma_f32 v[10:11], v[24:25], v[26:27], v[10:11] op_sel:[1,0,0] op_sel_hi:[1,1,1]
	v_pk_fma_f32 v[14:15], v[24:25], v[28:29], v[14:15] op_sel:[1,0,0] op_sel_hi:[1,1,1]
	v_pk_fma_f32 v[12:13], v[24:25], v[30:31], v[12:13] op_sel:[1,0,0] op_sel_hi:[1,1,1]
	v_pk_fma_f32 v[8:9], v[24:25], v[32:33], v[8:9] op_sel:[1,0,0] op_sel_hi:[1,1,1]
	s_cmpk_eq_i32 s22, 0x1000
	s_cbranch_scc0 .LBB0_22
	v_add_u32_e32 v6, s43, v17
	ds_write2st64_b32 v6, v10, v11 offset0:128 offset1:129
	ds_write2st64_b32 v6, v14, v15 offset0:130 offset1:131
	ds_write2st64_b32 v6, v12, v13 offset0:132 offset1:133
	ds_write2st64_b32 v6, v8, v9 offset0:134 offset1:135
	v_add_u32_e32 v6, s14, v66
	v_ashrrev_i32_e32 v7, 31, v6
	v_lshl_add_u64 v[6:7], v[6:7], 2, s[16:17]
	s_waitcnt lgkmcnt(0)
	s_barrier
	global_load_dword v16, v[6:7], off
	ds_read2st64_b32 v[8:9], v20 offset0:128 offset1:136
	ds_read2st64_b32 v[10:11], v20 offset0:144 offset1:152
	ds_read2st64_b32 v[12:13], v20 offset0:160 offset1:168
	ds_read2st64_b32 v[14:15], v20 offset0:176 offset1:184
	v_lshl_add_u64 v[6:7], v[4:5], 0, s[18:19]
	s_add_i32 s45, s45, s76
	v_lshl_add_u64 v[6:7], s[14:15], 2, v[6:7]
	s_cmpk_gt_i32 s45, 0x19f
	v_lshl_add_u64 v[6:7], v[6:7], 0, v[2:3]
	s_waitcnt vmcnt(0) lgkmcnt(3)
	v_add_f32_e32 v8, v16, v8
	v_add_f32_e32 v8, v8, v9
	s_waitcnt lgkmcnt(2)
	v_add_f32_e32 v8, v8, v10
	v_add_f32_e32 v8, v8, v11
	s_waitcnt lgkmcnt(1)
	v_add_f32_e32 v8, v8, v12
	v_add_f32_e32 v8, v8, v13
	s_waitcnt lgkmcnt(0)
	v_add_f32_e32 v8, v8, v14
	v_add_f32_e32 v8, v8, v15
	global_store_dword v[6:7], v8, off
	s_barrier
	s_cbranch_scc0 .LBB0_16
